# grid barrier replaced by the XCD-hierarchical barrier (XCC id from HW_REG_XCC_ID, per-XCC arrival counter, one L2 write-back per XCD by its last arriver, cross-XCC generation, per-workgroup agent acqu
# speedup vs baseline: 1.0556x; 1.0128x over previous
; DI int half_() { return __builtin_amdgcn_readfirstlane((int)(threadIdx.x >> 8)); }
; __global__ void __launch_bounds__(512, 2) mega(Params p_unused, int ph0, int ph1) {
;   __shared__ __attribute__((aligned(16))) unsigned char lds_all[LDS_BYTES];
;   unsigned char* ldsb = lds_all + half_() * LDS_HALF;
;   cg::grid_group grid = cg::this_grid();
;   for (int ph = ph0; ph < ph1; ++ph) {
;     const __attribute__((address_space(4))) Params* pp = (const __attribute__((address_space(4))) Params*)__builtin_amdgcn_kernarg_segment_ptr();
;     asm volatile("" : "+s"(pp));
;     PREF p = *pp;
;     if (ph1 < 0) grid.sync();
;     if (ph > ph0) grid_barrier(p.bar, (unsigned)(ph - ph0));
.LBB0_1:
	s_lshr_b32 s33, s0, 8
	v_readlane_b32 s0, v254, 1
	v_readlane_b32 s1, v254, 2
	s_add_u32 s2, s0, 0x1a8
	s_addc_u32 s3, s1, 0
	v_writelane_b32 v254, s2, 5
	v_lshrrev_b32_e32 v1, 20, v0
	v_lshrrev_b32_e32 v0, 10, v0
	v_writelane_b32 v254, s3, 6
	v_or_b32_e32 v0, v0, v1
	s_movk_i32 s2, 0x3ff
	v_and_or_b32 v0, v0, s2, v168
	v_readlane_b32 s8, v254, 3
	v_cmp_eq_u32_e64 s[2:3], 0, v0
	v_readlane_b32 s9, v254, 4
	s_load_dword s5, s[0:1], 0x1a8
	v_writelane_b32 v254, s2, 7
	s_cmp_lt_i32 s9, 0
	s_cselect_b64 s[0:1], -1, 0
	v_writelane_b32 v254, s3, 8
	v_cmp_eq_u32_e64 s[2:3], 0, v168
	s_waitcnt lgkmcnt(0)
	s_lshr_b32 s45, s5, 3
	s_mul_i32 s33, s33, 0x12400
	v_writelane_b32 v254, s2, 9
	v_cndmask_b32_e64 v0, 0, 1, s[0:1]
	v_cmp_ne_u32_e64 s[0:1], 1, v0
	v_writelane_b32 v254, s3, 10
	v_mbcnt_lo_u32_b32 v0, -1, 0
	v_readlane_b32 s4, v254, 0
	s_and_b32 s2, s4, 15
	s_xor_b32 s3, s2, 15
	s_add_i32 s3, s5, s3
	s_lshr_b32 s3, s3, 4
	s_lshl_b32 s2, s2, 6
	s_lshr_b32 s46, s4, 3
	s_cmpk_lt_u32 s4, 0x200
	v_writelane_b32 v254, s3, 11
	s_cselect_b64 s[6:7], -1, 0
	s_lshl_b32 s3, s4, 4
	s_and_b32 s47, s3, 0x70
	s_lshl_b32 s3, s4, 3
	s_lshl_b32 s48, s5, 3
	v_writelane_b32 v254, s6, 12
	s_cmpk_lt_i32 s4, 0x100
	s_mov_b32 s53, 0
	v_writelane_b32 v254, s7, 13
	s_cselect_b64 s[6:7], -1, 0
	v_writelane_b32 v254, s6, 14
	s_ashr_i32 s49, s48, 31
	s_lshl_b32 s64, s5, 9
	v_writelane_b32 v254, s7, 15
	s_add_i32 s6, s33, 0x12000
	v_writelane_b32 v254, s6, 16
	s_lshl_b32 s6, s4, 9
	v_writelane_b32 v254, s6, 17
	s_lshl_b64 s[6:7], s[48:49], 11
	v_writelane_b32 v254, s6, 18
	s_ashr_i32 s65, s64, 31
	s_lshl_b32 s70, s4, 1
	v_writelane_b32 v254, s7, 19
	v_writelane_b32 v254, s3, 20
	s_addk_i32 s3, 0x4000
	v_writelane_b32 v254, s3, 21
	s_lshl_b32 s3, s4, 8
	v_writelane_b32 v254, s3, 22
	s_lshl_b32 s3, s5, 8
	v_writelane_b32 v254, s3, 23
	s_add_i32 s3, s33, 0x4000
	v_writelane_b32 v254, s3, 24
	s_lshl_b32 s3, s4, 6
	v_writelane_b32 v254, s3, 25
	s_lshl_b64 s[6:7], s[64:65], 4
	v_writelane_b32 v254, s6, 26
	s_lshl_b32 s3, s5, 10
	s_lshl_b32 s71, s5, 1
	v_writelane_b32 v254, s7, 27
	s_lshl_b64 s[6:7], s[64:65], 5
	v_writelane_b32 v254, s6, 28
	s_lshl_b32 s81, s4, 7
	s_lshl_b32 s84, s5, 7
	v_writelane_b32 v254, s7, 29
	s_lshl_b64 s[6:7], s[48:49], 12
	v_writelane_b32 v254, s6, 30
	s_lshl_b32 s85, s5, 6
	s_movk_i32 s66, 0x200
	v_writelane_b32 v254, s7, 31
	v_writelane_b32 v254, s5, 32
	v_writelane_b32 v254, s3, 33
	s_lshl_b64 s[4:5], s[64:65], 2
	v_writelane_b32 v254, s4, 34
	v_and_b32_e32 v169, 0xff, v168
	s_movk_i32 s67, 0x100
	v_writelane_b32 v254, s5, 35
	v_writelane_b32 v254, s0, 36
	s_lshl_b64 s[72:73], s[64:65], 6
	v_mov_b32_e32 v1, 0
	v_writelane_b32 v254, s1, 37
	s_lshl_b32 s0, s2, 2
	v_writelane_b32 v254, s0, 38
	v_writelane_b32 v254, s45, 39
	v_writelane_b32 v254, s46, 40
	v_writelane_b32 v254, s47, 41
	s_mov_b32 s0, s48
	v_writelane_b32 v254, s0, 42
	s_mov_b32 s88, 0x10000
	v_mov_b32_e32 v170, 0x1000
	v_writelane_b32 v254, s1, 43
	s_mov_b32 s0, s64
	s_mov_b64 s[76:77], 0x80
	s_mov_b64 s[78:79], 0x40080
	s_mov_b64 s[42:43], 0x12b0100
	s_mov_b64 s[82:83], 0x100
	s_mov_b64 s[86:87], 0x40100
	s_mov_b64 s[90:91], 0x180
	s_movk_i32 s89, 0x180
	s_movk_i32 s92, 0x210
	s_movk_i32 s93, 0x80
	v_mov_b32_e32 v171, 0x3727c5ac
	s_mov_b32 s61, 0x800000
	s_movk_i32 s80, 0x1000
	s_mov_b64 s[50:51], 0x580100
	s_mov_b64 s[38:39], 0x980100
	s_mov_b64 s[4:5], 0x580180
	s_mov_b64 s[74:75], 0x980180
	s_movk_i32 s60, 0x1540
	s_movk_i32 s96, 0x300
	s_movk_i32 s97, 0x90
	s_mov_b32 s94, 0xff800000
	v_mbcnt_hi_u32_b32 v172, -1, v0
	v_mov_b32_e32 v163, 1.0
	s_mov_b64 s[2:3], 0xaa000
	v_mov_b32_e32 v173, 0x358637bd
	s_movk_i32 s95, 0x400
	s_mov_b64 s[6:7], 0x40180
	s_movk_i32 s58, 0xaa0
	s_movk_i32 s59, 0x600
	s_movk_i32 s54, 0x2a80
	v_mov_b32_e32 v174, 0x3c0881c4
	v_mov_b32_e32 v175, 0xbab64f3b
	v_mov_b32_e32 v176, 0xff800000
	v_mov_b32_e32 v177, 0x7f800000
	v_not_b32_e32 v178, 63
	v_not_b32_e32 v179, 31
	v_mov_b32_e32 v180, 0x7fc00000
	v_mov_b32_e32 v181, 0x37000000
	s_mov_b32 s34, s8
	v_writelane_b32 v254, s0, 44
	s_nop 1
	v_writelane_b32 v254, s1, 45
	s_getreg_b32 s0, hwreg(HW_REG_XCC_ID, 0, 4)
	v_writelane_b32 v254, s0, 61
	s_mov_b32 s1, 0
	v_writelane_b32 v254, s1, 62
	v_writelane_b32 v254, s1, 63
	s_nop 0
	v_readlane_b32 s12, v254, 9
	v_readlane_b32 s13, v254, 10
	s_and_saveexec_b64 s[14:15], s[12:13]
	s_cbranch_execz .Lmy_xb_posted
	v_readlane_b32 s12, v254, 1
	v_readlane_b32 s13, v254, 2
	s_load_dwordx2 s[12:13], s[12:13], 0x198
	s_lshl_b32 s0, s0, 8
	s_addk_i32 s0, 0x400
	v_mov_b32_e32 v0, s0
	v_mov_b32_e32 v2, 1
	s_waitcnt lgkmcnt(0)
	global_atomic_add v0, v2, s[12:13]
.Lmy_xb_posted:
	s_or_b64 exec, exec, s[14:15]
	s_branch .LBB0_4

; DI void grid_barrier(unsigned* bar, unsigned gen) {
;   asm volatile("s_waitcnt vmcnt(0)" ::: "memory");
;   __syncthreads();
;   if (threadIdx.x == 0) {
;     __builtin_amdgcn_fence(__ATOMIC_RELEASE, "agent");
;     const unsigned grp = blockIdx.x & 15u;
;     const unsigned nblk = (gridDim.x + 15u - grp) >> 4;
;     unsigned old = __hip_atomic_fetch_add(bar + 64 * (1 + grp), 1u, __ATOMIC_RELAXED, __HIP_MEMORY_SCOPE_AGENT);
;     if (old + 1u == nblk * gen) {
;       unsigned g = __hip_atomic_fetch_add(bar, 1u, __ATOMIC_RELAXED, __HIP_MEMORY_SCOPE_AGENT);
;       if (g + 1u == 16u * gen) {
;         for (int i = 0; i < 16; ++i) __hip_atomic_store(bar + 64 * (17 + i), gen, __ATOMIC_RELAXED, __HIP_MEMORY_SCOPE_AGENT);
;       }
;     }
;     while (__hip_atomic_load(bar + 64 * (17 + grp), __ATOMIC_RELAXED, __HIP_MEMORY_SCOPE_AGENT) < gen) __builtin_amdgcn_s_sleep(4);
;     __builtin_amdgcn_fence(__ATOMIC_ACQUIRE, "agent");
;   }
;   __syncthreads();
; }
.LBB0_16:
	v_readlane_b32 s0, v254, 3
	s_cmp_le_i32 s34, s0
	v_readlane_b32 s1, v254, 4
	s_cbranch_scc1 .LBB0_29
	s_waitcnt vmcnt(0)
	v_readlane_b32 s0, v254, 9
	v_readlane_b32 s1, v254, 10
	s_barrier
	s_and_saveexec_b64 s[8:9], s[0:1]
	s_cbranch_execz .LBB0_28
	v_readlane_b32 s0, v254, 46
	v_readlane_b32 s1, v254, 47
	s_load_dwordx2 s[12:13], s[0:1], 0x198
	v_readlane_b32 s0, v254, 3
	s_sub_i32 s20, s34, s0
	v_readlane_b32 s14, v254, 61
	v_readlane_b32 s15, v254, 62
	v_readlane_b32 s16, v254, 63
	s_lshl_b32 s17, s14, 8
	v_mov_b32_e32 v2, 1
	s_waitcnt lgkmcnt(0)
	s_cmp_lg_u32 s15, 0
	s_cbranch_scc1 .Lmy_xb_go
	v_mov_b32_e32 v0, 0x400
.Lmy_xb_census:
	global_load_dword v4, v0, s[12:13] offset:0 sc1
	global_load_dword v5, v0, s[12:13] offset:256 sc1
	global_load_dword v6, v0, s[12:13] offset:512 sc1
	global_load_dword v7, v0, s[12:13] offset:768 sc1
	global_load_dword v8, v0, s[12:13] offset:1024 sc1
	global_load_dword v9, v0, s[12:13] offset:1280 sc1
	global_load_dword v10, v0, s[12:13] offset:1536 sc1
	global_load_dword v11, v0, s[12:13] offset:1792 sc1
	global_load_dword v12, v0, s[12:13] offset:2048 sc1
	global_load_dword v13, v0, s[12:13] offset:2304 sc1
	global_load_dword v14, v0, s[12:13] offset:2560 sc1
	global_load_dword v15, v0, s[12:13] offset:2816 sc1
	global_load_dword v16, v0, s[12:13] offset:3072 sc1
	global_load_dword v17, v0, s[12:13] offset:3328 sc1
	global_load_dword v18, v0, s[12:13] offset:3584 sc1
	global_load_dword v19, v0, s[12:13] offset:3840 sc1
	v_mov_b32_e32 v3, s17
	v_add_u32_e32 v3, 0x400, v3
	global_load_dword v3, v3, s[12:13] sc1
	s_waitcnt vmcnt(0)
	v_mov_b32_e32 v20, 0
	v_mov_b32_e32 v22, 0
	v_add_u32_e32 v20, v20, v4
	v_min_u32_e32 v21, 1, v4
	v_add_u32_e32 v22, v22, v21
	v_add_u32_e32 v20, v20, v5
	v_min_u32_e32 v21, 1, v5
	v_add_u32_e32 v22, v22, v21
	v_add_u32_e32 v20, v20, v6
	v_min_u32_e32 v21, 1, v6
	v_add_u32_e32 v22, v22, v21
	v_add_u32_e32 v20, v20, v7
	v_min_u32_e32 v21, 1, v7
	v_add_u32_e32 v22, v22, v21
	v_add_u32_e32 v20, v20, v8
	v_min_u32_e32 v21, 1, v8
	v_add_u32_e32 v22, v22, v21
	v_add_u32_e32 v20, v20, v9
	v_min_u32_e32 v21, 1, v9
	v_add_u32_e32 v22, v22, v21
	v_add_u32_e32 v20, v20, v10
	v_min_u32_e32 v21, 1, v10
	v_add_u32_e32 v22, v22, v21
	v_add_u32_e32 v20, v20, v11
	v_min_u32_e32 v21, 1, v11
	v_add_u32_e32 v22, v22, v21
	v_add_u32_e32 v20, v20, v12
	v_min_u32_e32 v21, 1, v12
	v_add_u32_e32 v22, v22, v21
	v_add_u32_e32 v20, v20, v13
	v_min_u32_e32 v21, 1, v13
	v_add_u32_e32 v22, v22, v21
	v_add_u32_e32 v20, v20, v14
	v_min_u32_e32 v21, 1, v14
	v_add_u32_e32 v22, v22, v21
	v_add_u32_e32 v20, v20, v15
	v_min_u32_e32 v21, 1, v15
	v_add_u32_e32 v22, v22, v21
	v_add_u32_e32 v20, v20, v16
	v_min_u32_e32 v21, 1, v16
	v_add_u32_e32 v22, v22, v21
	v_add_u32_e32 v20, v20, v17
	v_min_u32_e32 v21, 1, v17
	v_add_u32_e32 v22, v22, v21
	v_add_u32_e32 v20, v20, v18
	v_min_u32_e32 v21, 1, v18
	v_add_u32_e32 v22, v22, v21
	v_add_u32_e32 v20, v20, v19
	v_min_u32_e32 v21, 1, v19
	v_add_u32_e32 v22, v22, v21
	v_readfirstlane_b32 s18, v20
	v_readfirstlane_b32 s16, v22
	v_readfirstlane_b32 s15, v3
	v_readlane_b32 s21, v254, 32
	s_cmp_eq_u32 s18, s21
	s_cbranch_scc1 .Lmy_xb_census_done
	s_sleep 1
	s_branch .Lmy_xb_census
.Lmy_xb_census_done:
	v_writelane_b32 v254, s15, 62
	v_writelane_b32 v254, s16, 63
.Lmy_xb_go:
	v_mov_b32_e32 v0, s17
	v_add_u32_e32 v0, 0x1400, v0
	global_atomic_add v3, v0, v2, s[12:13] sc0
	s_waitcnt vmcnt(0)
	v_readfirstlane_b32 s18, v3
	s_add_i32 s18, s18, 1
	s_mul_i32 s19, s20, s15
	s_cmp_eq_u32 s18, s19
	s_cbranch_scc0 .Lmy_xb_follow
	buffer_wbl2 sc1
	s_waitcnt vmcnt(0)
	v_mov_b32_e32 v0, 0x3400
	global_atomic_add v3, v0, v2, s[12:13] sc0
	s_waitcnt vmcnt(0)
	v_readfirstlane_b32 s18, v3
	s_add_i32 s18, s18, 1
	s_mul_i32 s19, s20, s16
	v_mov_b32_e32 v0, 0x3500
	s_cmp_eq_u32 s18, s19
	s_cbranch_scc0 .Lmy_xb_spin_top
	global_atomic_add v0, v2, s[12:13]
	s_branch .Lmy_xb_lead_acq
.Lmy_xb_spin_top:
	s_sleep 1
	global_load_dword v3, v0, s[12:13] sc1
	s_waitcnt vmcnt(0)
	v_readfirstlane_b32 s18, v3
	s_cmp_lt_u32 s18, s20
	s_cbranch_scc1 .Lmy_xb_spin_top
.Lmy_xb_lead_acq:
	buffer_inv sc1
	v_mov_b32_e32 v0, s17
	v_add_u32_e32 v0, 0x2400, v0
	global_atomic_add v0, v2, s[12:13]
	s_waitcnt vmcnt(0)
	s_branch .LBB0_28
.Lmy_xb_follow:
	v_mov_b32_e32 v0, s17
	v_add_u32_e32 v0, 0x2400, v0
.Lmy_xb_spin_loc:
	s_sleep 1
	global_load_dword v3, v0, s[12:13] sc1
	s_waitcnt vmcnt(0)
	v_readfirstlane_b32 s18, v3
	s_cmp_lt_u32 s18, s20
	s_cbranch_scc1 .Lmy_xb_spin_loc
	buffer_inv sc1
	s_waitcnt vmcnt(0)
